# nt policy on the gate/up epilogue HM stores (written once, read next phase)
# baseline (speedup 1.0000x reference)
; DI float ss_get(const ssacc_t* p) { const ssacc_t v = *p; return (float)(unsigned)(v >> 32) + (float)(unsigned)(v & 0xffffffffull) * 2.3283064365386963e-10f; }
; DI unsigned cvtpk(float lo, float hi) { f32x2 v = {lo, hi}; bf16x2_t b = __builtin_convertvector(v, bf16x2_t); return __builtin_bit_cast(unsigned, b); }
; DI float sigmoidf_(float x) { return __builtin_amdgcn_rcpf(1.f + fexp2(-LOG2E * x)); }
;     DI void operator()(const Acc& acc, const Unit& u, int wr, int wc, int fr, int fq) const {
;     ...
;         for (int ai = 0; ai < 2; ++ai)
; #pragma unroll
;             for (int m = 0; m < 4; ++m) {
;                 asm volatile("" ::: "memory");
;                 const int row = u.pm * 256 + ai * 128 + wr * 64 + m * 16 + fr;
;                 const float rs = rsqrtf(ss_get(ssx1 + row) * (1.f / 2048.f) + EPS_);
; #pragma unroll
;                 for (int bj = 0; bj < 2; ++bj) {
;                     const f32x4 v0 = acc[ai][bj][m][0] * rs, v1 = acc[ai][bj][m][1] * rs;
;                     const int i0 = (u.pn * 256 + bj * 128 + wc * 32 + 8 * fq) >> 1;
;                     const float o0 = v0[0] * sigmoidf_(v0[0]) * v0[1], o1 = v0[2] * sigmoidf_(v0[2]) * v0[3];
;                     const float o2 = v1[0] * sigmoidf_(v1[0]) * v1[1], o3 = v1[2] * sigmoidf_(v1[2]) * v1[3];
;                     u32x2 w; w.x = cvtpk(o0, o1); w.y = cvtpk(o2, o3);
;                     *(u32x2*)(HM + (size_t)row * DFF_ + i0) = w;
;                 }
;             }
.LBB0_1368:
	v_lshl_add_u32 v142, s41, 8, v144
	v_ashrrev_i32_e32 v143, 31, v142
	v_lshl_add_u64 v[148:149], v[142:143], 3, s[44:45]
	global_load_dwordx2 v[212:213], v[148:149], off
	global_load_dwordx2 v[214:215], v[148:149], off offset:128
	global_load_dwordx2 v[216:217], v[148:149], off offset:256
	global_load_dwordx2 v[218:219], v[148:149], off offset:384
	global_load_dwordx2 v[220:221], v[148:149], off offset:1024
	global_load_dwordx2 v[222:223], v[148:149], off offset:1152
	global_load_dwordx2 v[224:225], v[148:149], off offset:1280
	global_load_dwordx2 v[226:227], v[148:149], off offset:1408
	s_min_u32 s14, s88, 32
	s_sub_i32 s15, 32, s14
	v_lshl_or_b32 v152, s40, 8, v146
	s_movk_i32 s4, 0x2c00
	s_waitcnt vmcnt(7)
	v_mov_b32_e32 v148, v212
	v_mov_b32_e32 v149, v213
	v_mov_b32_e32 v128, v149
	v_lshlrev_b64 v[150:151], s14, v[128:129]
	v_min_u32_e32 v128, 1, v150
	v_or_b32_e32 v128, v151, v128
	v_cvt_f32_u32_e32 v128, v128
	v_cvt_f32_u32_e32 v143, v148
	v_ldexp_f32 v128, v128, s15
	v_fmac_f32_e32 v128, 0x2f800000, v143
	v_fmamk_f32 v128, v128, 0x3a000000, v195
	v_cmp_gt_f32_e32 vcc, s27, v128
	v_mul_f32_e32 v143, 0x4b800000, v128
	s_nop 0
	v_cndmask_b32_e32 v128, v128, v143, vcc
	v_rsq_f32_e32 v128, v128
	s_nop 0
	v_mul_f32_e32 v143, 0x45800000, v128
	v_cndmask_b32_e32 v128, v128, v143, vcc
	v_pk_mul_f32 v[120:121], v[120:121], v[128:129] op_sel_hi:[1,0]
	v_pk_mul_f32 v[148:149], v[122:123], v[128:129] op_sel_hi:[1,0]
	v_mul_f32_e32 v123, 0xbfb8aa3b, v120
	v_exp_f32_e32 v123, v123
	v_pk_mul_f32 v[124:125], v[124:125], v[128:129] op_sel_hi:[1,0]
	v_ashrrev_i32_e32 v122, 1, v152
	v_mov_b32_e32 v152, v120
	v_add_f32_e32 v123, 1.0, v123
	v_rcp_f32_e32 v150, v123
	v_mul_f32_e32 v123, 0xbfb8aa3b, v148
	v_exp_f32_e32 v123, v123
	v_mov_b32_e32 v153, v148
	v_pk_mul_f32 v[126:127], v[126:127], v[128:129] op_sel_hi:[1,0]
	v_mov_b32_e32 v148, v121
	v_add_f32_e32 v123, 1.0, v123
	v_rcp_f32_e32 v151, v123
	v_mul_f32_e32 v123, 0xbfb8aa3b, v124
	v_exp_f32_e32 v123, v123
	v_pk_mul_f32 v[118:119], v[118:119], v[128:129] op_sel_hi:[1,0]
	v_pk_mul_f32 v[150:151], v[152:153], v[150:151]
	v_pk_mul_f32 v[116:117], v[116:117], v[128:129] op_sel_hi:[1,0]
	v_add_f32_e32 v123, 1.0, v123
	v_pk_mul_f32 v[120:121], v[148:149], v[150:151]
	v_rcp_f32_e32 v148, v123
	v_mul_f32_e32 v123, 0xbfb8aa3b, v126
	v_exp_f32_e32 v123, v123
	v_mov_b32_e32 v150, v124
	v_mov_b32_e32 v151, v126
	v_mov_b32_e32 v126, v125
	v_add_f32_e32 v123, 1.0, v123
	v_rcp_f32_e32 v149, v123
	v_ashrrev_i32_e32 v123, 31, v122
	v_lshlrev_b64 v[122:123], 1, v[122:123]
	v_pk_mul_f32 v[114:115], v[114:115], v[128:129] op_sel_hi:[1,0]
	v_pk_mul_f32 v[148:149], v[150:151], v[148:149]
	v_pk_mul_f32 v[112:113], v[112:113], v[128:129] op_sel_hi:[1,0]
	v_pk_mul_f32 v[124:125], v[126:127], v[148:149]
	v_cvt_pk_bf16_f32 v126, v120, v121
	v_mov_b64_e32 v[120:121], s[50:51]
	v_cvt_pk_bf16_f32 v127, v124, v125
	v_mad_i64_i32 v[124:125], s[16:17], v142, s4, v[120:121]
	v_lshl_add_u64 v[124:125], v[124:125], 0, v[122:123]
	global_store_dwordx2 v[124:125], v[126:127], off nt
	v_mul_f32_e32 v126, 0xbfb8aa3b, v116
	v_mul_f32_e32 v127, 0xbfb8aa3b, v118
	v_exp_f32_e32 v126, v126
	v_exp_f32_e32 v127, v127
	v_mov_b32_e32 v148, v116
	v_mov_b32_e32 v149, v118
	v_add_f32_e32 v126, 1.0, v126
	v_add_f32_e32 v127, 1.0, v127
	v_rcp_f32_e32 v126, v126
	v_rcp_f32_e32 v127, v127
	v_mov_b32_e32 v118, v117
	v_pk_mul_f32 v[126:127], v[148:149], v[126:127]
	s_nop 0
	v_pk_mul_f32 v[116:117], v[118:119], v[126:127]
	v_mul_f32_e32 v118, 0xbfb8aa3b, v112
	v_mul_f32_e32 v119, 0xbfb8aa3b, v114
	v_exp_f32_e32 v118, v118
	v_exp_f32_e32 v119, v119
	v_mov_b32_e32 v126, v112
	v_mov_b32_e32 v127, v114
	v_add_f32_e32 v118, 1.0, v118
	v_add_f32_e32 v119, 1.0, v119
	v_rcp_f32_e32 v118, v118
	v_rcp_f32_e32 v119, v119
	v_mov_b32_e32 v114, v113
	v_pk_mul_f32 v[118:119], v[126:127], v[118:119]
	s_nop 0
	v_pk_mul_f32 v[112:113], v[114:115], v[118:119]
	v_cvt_pk_bf16_f32 v114, v116, v117
	v_cvt_pk_bf16_f32 v115, v112, v113
	v_or_b32_e32 v112, 16, v142
	global_store_dwordx2 v[124:125], v[114:115], off offset:128 nt
	v_ashrrev_i32_e32 v113, 31, v112
	s_waitcnt vmcnt(8)
	v_mov_b32_e32 v114, v214
	v_mov_b32_e32 v115, v215
	v_mov_b32_e32 v128, v115
	v_lshlrev_b64 v[116:117], s14, v[128:129]
	v_min_u32_e32 v113, 1, v116
	v_or_b32_e32 v113, v117, v113
	v_cvt_f32_u32_e32 v113, v113
	v_cvt_f32_u32_e32 v114, v114
	v_ldexp_f32 v113, v113, s15
	v_fmac_f32_e32 v113, 0x2f800000, v114
	v_fmamk_f32 v113, v113, 0x3a000000, v195
	v_cmp_gt_f32_e32 vcc, s27, v113
	v_mul_f32_e32 v114, 0x4b800000, v113
	s_nop 0
	v_cndmask_b32_e32 v113, v113, v114, vcc
	v_rsq_f32_e32 v113, v113
	s_nop 0
	v_mul_f32_e32 v114, 0x45800000, v113
	v_cndmask_b32_e32 v114, v113, v114, vcc
	v_pk_mul_f32 v[108:109], v[108:109], v[114:115] op_sel_hi:[1,0]
	v_pk_mul_f32 v[110:111], v[110:111], v[114:115] op_sel_hi:[1,0]
	v_mul_f32_e32 v113, 0xbfb8aa3b, v108
	v_exp_f32_e32 v113, v113
	v_mov_b32_e32 v118, v108
	v_mov_b32_e32 v119, v110
	v_pk_mul_f32 v[106:107], v[106:107], v[114:115] op_sel_hi:[1,0]
	v_add_f32_e32 v113, 1.0, v113
	v_rcp_f32_e32 v116, v113
	v_mul_f32_e32 v113, 0xbfb8aa3b, v110
	v_exp_f32_e32 v113, v113
	v_pk_mul_f32 v[104:105], v[104:105], v[114:115] op_sel_hi:[1,0]
	v_mov_b32_e32 v110, v109
	v_pk_mul_f32 v[102:103], v[102:103], v[114:115] op_sel_hi:[1,0]
	v_add_f32_e32 v113, 1.0, v113
	v_rcp_f32_e32 v117, v113
	v_pk_mul_f32 v[100:101], v[100:101], v[114:115] op_sel_hi:[1,0]
	v_pk_mul_f32 v[98:99], v[98:99], v[114:115] op_sel_hi:[1,0]
	v_pk_mul_f32 v[96:97], v[96:97], v[114:115] op_sel_hi:[1,0]
	v_pk_mul_f32 v[116:117], v[118:119], v[116:117]
	s_nop 0
	v_pk_mul_f32 v[108:109], v[110:111], v[116:117]
; DI float ss_get(const ssacc_t* p) { const ssacc_t v = *p; return (float)(unsigned)(v >> 32) + (float)(unsigned)(v & 0xffffffffull) * 2.3283064365386963e-10f; }
; DI unsigned cvtpk(float lo, float hi) { f32x2 v = {lo, hi}; bf16x2_t b = __builtin_convertvector(v, bf16x2_t); return __builtin_bit_cast(unsigned, b); }
; DI float sigmoidf_(float x) { return __builtin_amdgcn_rcpf(1.f + fexp2(-LOG2E * x)); }
;     DI void operator()(const Acc& acc, const Unit& u, int wr, int wc, int fr, int fq) const {
;     ...
;         for (int ai = 0; ai < 2; ++ai)
; #pragma unroll
;             for (int m = 0; m < 4; ++m) {
;                 asm volatile("" ::: "memory");
;                 const int row = u.pm * 256 + ai * 128 + wr * 64 + m * 16 + fr;
;                 const float rs = rsqrtf(ss_get(ssx1 + row) * (1.f / 2048.f) + EPS_);
; #pragma unroll
;                 for (int bj = 0; bj < 2; ++bj) {
;                     const f32x4 v0 = acc[ai][bj][m][0] * rs, v1 = acc[ai][bj][m][1] * rs;
;                     const int i0 = (u.pn * 256 + bj * 128 + wc * 32 + 8 * fq) >> 1;
;                     const float o0 = v0[0] * sigmoidf_(v0[0]) * v0[1], o1 = v0[2] * sigmoidf_(v0[2]) * v0[3];
;                     const float o2 = v1[0] * sigmoidf_(v1[0]) * v1[1], o3 = v1[2] * sigmoidf_(v1[2]) * v1[3];
;                     u32x2 w; w.x = cvtpk(o0, o1); w.y = cvtpk(o2, o3);
;                     *(u32x2*)(HM + (size_t)row * DFF_ + i0) = w;
;                 }
;             }
	v_mul_f32_e32 v110, 0xbfb8aa3b, v104
	v_mul_f32_e32 v111, 0xbfb8aa3b, v106
	v_exp_f32_e32 v110, v110
	v_exp_f32_e32 v111, v111
	v_mov_b32_e32 v116, v104
	v_mov_b32_e32 v117, v106
	v_add_f32_e32 v110, 1.0, v110
	v_add_f32_e32 v111, 1.0, v111
	v_rcp_f32_e32 v110, v110
	v_rcp_f32_e32 v111, v111
	v_mov_b32_e32 v106, v105
	v_pk_mul_f32 v[110:111], v[116:117], v[110:111]
	s_nop 0
	v_pk_mul_f32 v[104:105], v[106:107], v[110:111]
	v_cvt_pk_bf16_f32 v106, v108, v109
	v_cvt_pk_bf16_f32 v107, v104, v105
	v_mad_i64_i32 v[104:105], s[16:17], v112, s4, v[120:121]
	v_lshl_add_u64 v[104:105], v[104:105], 0, v[122:123]
	global_store_dwordx2 v[104:105], v[106:107], off nt
	v_mul_f32_e32 v106, 0xbfb8aa3b, v100
	v_mul_f32_e32 v107, 0xbfb8aa3b, v102
	v_exp_f32_e32 v106, v106
	v_exp_f32_e32 v107, v107
	v_mov_b32_e32 v108, v100
	v_mov_b32_e32 v109, v102
	v_add_f32_e32 v106, 1.0, v106
	v_add_f32_e32 v107, 1.0, v107
	v_rcp_f32_e32 v106, v106
	v_rcp_f32_e32 v107, v107
	v_mov_b32_e32 v102, v101
	v_pk_mul_f32 v[106:107], v[108:109], v[106:107]
	s_nop 0
	v_pk_mul_f32 v[100:101], v[102:103], v[106:107]
	v_mul_f32_e32 v102, 0xbfb8aa3b, v96
	v_mul_f32_e32 v103, 0xbfb8aa3b, v98
	v_exp_f32_e32 v102, v102
	v_exp_f32_e32 v103, v103
	v_mov_b32_e32 v106, v96
	v_mov_b32_e32 v107, v98
	v_add_f32_e32 v102, 1.0, v102
	v_add_f32_e32 v103, 1.0, v103
	v_rcp_f32_e32 v102, v102
	v_rcp_f32_e32 v103, v103
	v_mov_b32_e32 v98, v97
	v_pk_mul_f32 v[102:103], v[106:107], v[102:103]
	s_nop 0
	v_pk_mul_f32 v[96:97], v[98:99], v[102:103]
	v_cvt_pk_bf16_f32 v98, v100, v101
	v_cvt_pk_bf16_f32 v99, v96, v97
	v_or_b32_e32 v96, 32, v142
	global_store_dwordx2 v[104:105], v[98:99], off offset:128 nt
	v_ashrrev_i32_e32 v97, 31, v96
	s_waitcnt vmcnt(9)
	v_mov_b32_e32 v98, v216
	v_mov_b32_e32 v99, v217
	v_mov_b32_e32 v128, v99
	v_lshlrev_b64 v[100:101], s14, v[128:129]
	v_min_u32_e32 v97, 1, v100
	v_or_b32_e32 v97, v101, v97
	v_cvt_f32_u32_e32 v97, v97
	v_cvt_f32_u32_e32 v98, v98
	v_ldexp_f32 v97, v97, s15
	v_fmac_f32_e32 v97, 0x2f800000, v98
	v_fmamk_f32 v97, v97, 0x3a000000, v195
	v_cmp_gt_f32_e32 vcc, s27, v97
	v_mul_f32_e32 v98, 0x4b800000, v97
	s_nop 0
	v_cndmask_b32_e32 v97, v97, v98, vcc
	v_rsq_f32_e32 v97, v97
	s_nop 0
	v_mul_f32_e32 v98, 0x45800000, v97
	v_cndmask_b32_e32 v98, v97, v98, vcc
	v_pk_mul_f32 v[92:93], v[92:93], v[98:99] op_sel_hi:[1,0]
	v_pk_mul_f32 v[94:95], v[94:95], v[98:99] op_sel_hi:[1,0]
	v_mul_f32_e32 v97, 0xbfb8aa3b, v92
	v_exp_f32_e32 v97, v97
	v_mov_b32_e32 v102, v92
	v_mov_b32_e32 v103, v94
	v_pk_mul_f32 v[90:91], v[90:91], v[98:99] op_sel_hi:[1,0]
	v_add_f32_e32 v97, 1.0, v97
	v_rcp_f32_e32 v100, v97
	v_mul_f32_e32 v97, 0xbfb8aa3b, v94
	v_exp_f32_e32 v97, v97
	v_pk_mul_f32 v[88:89], v[88:89], v[98:99] op_sel_hi:[1,0]
	v_mov_b32_e32 v94, v93
	v_pk_mul_f32 v[86:87], v[86:87], v[98:99] op_sel_hi:[1,0]
	v_add_f32_e32 v97, 1.0, v97
	v_rcp_f32_e32 v101, v97
	v_pk_mul_f32 v[84:85], v[84:85], v[98:99] op_sel_hi:[1,0]
	v_pk_mul_f32 v[82:83], v[82:83], v[98:99] op_sel_hi:[1,0]
	v_pk_mul_f32 v[80:81], v[80:81], v[98:99] op_sel_hi:[1,0]
	v_pk_mul_f32 v[100:101], v[102:103], v[100:101]
	s_nop 0
	v_pk_mul_f32 v[92:93], v[94:95], v[100:101]
	v_mul_f32_e32 v94, 0xbfb8aa3b, v88
	v_mul_f32_e32 v95, 0xbfb8aa3b, v90
	v_exp_f32_e32 v94, v94
	v_exp_f32_e32 v95, v95
	v_mov_b32_e32 v100, v88
	v_mov_b32_e32 v101, v90
	v_add_f32_e32 v94, 1.0, v94
	v_add_f32_e32 v95, 1.0, v95
	v_rcp_f32_e32 v94, v94
	v_rcp_f32_e32 v95, v95
	v_mov_b32_e32 v90, v89
	v_pk_mul_f32 v[94:95], v[100:101], v[94:95]
	s_nop 0
	v_pk_mul_f32 v[88:89], v[90:91], v[94:95]
	v_cvt_pk_bf16_f32 v90, v92, v93
	v_cvt_pk_bf16_f32 v91, v88, v89
	v_mad_i64_i32 v[88:89], s[16:17], v96, s4, v[120:121]
	v_lshl_add_u64 v[88:89], v[88:89], 0, v[122:123]
	global_store_dwordx2 v[88:89], v[90:91], off nt
	v_mul_f32_e32 v90, 0xbfb8aa3b, v84
	v_mul_f32_e32 v91, 0xbfb8aa3b, v86
	v_exp_f32_e32 v90, v90
	v_exp_f32_e32 v91, v91
	v_mov_b32_e32 v92, v84
	v_mov_b32_e32 v93, v86
	v_add_f32_e32 v90, 1.0, v90
	v_add_f32_e32 v91, 1.0, v91
	v_rcp_f32_e32 v90, v90
	v_rcp_f32_e32 v91, v91
	v_mov_b32_e32 v86, v85
	v_pk_mul_f32 v[90:91], v[92:93], v[90:91]
	s_nop 0
	v_pk_mul_f32 v[84:85], v[86:87], v[90:91]
	v_mul_f32_e32 v86, 0xbfb8aa3b, v80
	v_mul_f32_e32 v87, 0xbfb8aa3b, v82
	v_exp_f32_e32 v86, v86
	v_exp_f32_e32 v87, v87
	v_mov_b32_e32 v90, v80
	v_mov_b32_e32 v91, v82
	v_add_f32_e32 v86, 1.0, v86
	v_add_f32_e32 v87, 1.0, v87
	v_rcp_f32_e32 v86, v86
	v_rcp_f32_e32 v87, v87
	v_mov_b32_e32 v82, v81
	v_pk_mul_f32 v[86:87], v[90:91], v[86:87]
	s_nop 0
	v_pk_mul_f32 v[80:81], v[82:83], v[86:87]
	v_cvt_pk_bf16_f32 v82, v84, v85
	v_cvt_pk_bf16_f32 v83, v80, v81
	v_or_b32_e32 v80, 48, v142
	global_store_dwordx2 v[88:89], v[82:83], off offset:128 nt
	v_ashrrev_i32_e32 v81, 31, v80
	s_waitcnt vmcnt(10)
; DI float ss_get(const ssacc_t* p) { const ssacc_t v = *p; return (float)(unsigned)(v >> 32) + (float)(unsigned)(v & 0xffffffffull) * 2.3283064365386963e-10f; }
; DI unsigned cvtpk(float lo, float hi) { f32x2 v = {lo, hi}; bf16x2_t b = __builtin_convertvector(v, bf16x2_t); return __builtin_bit_cast(unsigned, b); }
; DI float sigmoidf_(float x) { return __builtin_amdgcn_rcpf(1.f + fexp2(-LOG2E * x)); }
;     DI void operator()(const Acc& acc, const Unit& u, int wr, int wc, int fr, int fq) const {
;     ...
;         for (int ai = 0; ai < 2; ++ai)
; #pragma unroll
;             for (int m = 0; m < 4; ++m) {
;                 asm volatile("" ::: "memory");
;                 const int row = u.pm * 256 + ai * 128 + wr * 64 + m * 16 + fr;
;                 const float rs = rsqrtf(ss_get(ssx1 + row) * (1.f / 2048.f) + EPS_);
; #pragma unroll
;                 for (int bj = 0; bj < 2; ++bj) {
;                     const f32x4 v0 = acc[ai][bj][m][0] * rs, v1 = acc[ai][bj][m][1] * rs;
;                     const int i0 = (u.pn * 256 + bj * 128 + wc * 32 + 8 * fq) >> 1;
;                     const float o0 = v0[0] * sigmoidf_(v0[0]) * v0[1], o1 = v0[2] * sigmoidf_(v0[2]) * v0[3];
;                     const float o2 = v1[0] * sigmoidf_(v1[0]) * v1[1], o3 = v1[2] * sigmoidf_(v1[2]) * v1[3];
;                     u32x2 w; w.x = cvtpk(o0, o1); w.y = cvtpk(o2, o3);
;                     *(u32x2*)(HM + (size_t)row * DFF_ + i0) = w;
;                 }
;             }
	v_mov_b32_e32 v82, v218
	v_mov_b32_e32 v83, v219
	v_mov_b32_e32 v128, v83
	v_lshlrev_b64 v[84:85], s14, v[128:129]
	v_min_u32_e32 v81, 1, v84
	v_or_b32_e32 v81, v85, v81
	v_cvt_f32_u32_e32 v81, v81
	v_cvt_f32_u32_e32 v82, v82
	v_ldexp_f32 v81, v81, s15
	v_fmac_f32_e32 v81, 0x2f800000, v82
	v_fmamk_f32 v81, v81, 0x3a000000, v195
	v_cmp_gt_f32_e32 vcc, s27, v81
	v_mul_f32_e32 v82, 0x4b800000, v81
	s_nop 0
	v_cndmask_b32_e32 v81, v81, v82, vcc
	v_rsq_f32_e32 v81, v81
	s_nop 0
	v_mul_f32_e32 v82, 0x45800000, v81
	v_cndmask_b32_e32 v82, v81, v82, vcc
	v_pk_mul_f32 v[76:77], v[76:77], v[82:83] op_sel_hi:[1,0]
	v_pk_mul_f32 v[78:79], v[78:79], v[82:83] op_sel_hi:[1,0]
	v_mul_f32_e32 v81, 0xbfb8aa3b, v76
	v_exp_f32_e32 v81, v81
	v_mov_b32_e32 v86, v76
	v_mov_b32_e32 v87, v78
	v_pk_mul_f32 v[74:75], v[74:75], v[82:83] op_sel_hi:[1,0]
	v_add_f32_e32 v81, 1.0, v81
	v_rcp_f32_e32 v84, v81
	v_mul_f32_e32 v81, 0xbfb8aa3b, v78
	v_exp_f32_e32 v81, v81
	v_pk_mul_f32 v[72:73], v[72:73], v[82:83] op_sel_hi:[1,0]
	v_mov_b32_e32 v78, v77
	v_pk_mul_f32 v[70:71], v[70:71], v[82:83] op_sel_hi:[1,0]
	v_add_f32_e32 v81, 1.0, v81
	v_rcp_f32_e32 v85, v81
	v_pk_mul_f32 v[68:69], v[68:69], v[82:83] op_sel_hi:[1,0]
	v_pk_mul_f32 v[66:67], v[66:67], v[82:83] op_sel_hi:[1,0]
	v_pk_mul_f32 v[64:65], v[64:65], v[82:83] op_sel_hi:[1,0]
	v_pk_mul_f32 v[84:85], v[86:87], v[84:85]
	s_nop 0
	v_pk_mul_f32 v[76:77], v[78:79], v[84:85]
	v_mul_f32_e32 v78, 0xbfb8aa3b, v72
	v_mul_f32_e32 v79, 0xbfb8aa3b, v74
	v_exp_f32_e32 v78, v78
	v_exp_f32_e32 v79, v79
	v_mov_b32_e32 v84, v72
	v_mov_b32_e32 v85, v74
	v_add_f32_e32 v78, 1.0, v78
	v_add_f32_e32 v79, 1.0, v79
	v_rcp_f32_e32 v78, v78
	v_rcp_f32_e32 v79, v79
	v_mov_b32_e32 v74, v73
	v_pk_mul_f32 v[78:79], v[84:85], v[78:79]
	s_nop 0
	v_pk_mul_f32 v[72:73], v[74:75], v[78:79]
	v_cvt_pk_bf16_f32 v74, v76, v77
	v_cvt_pk_bf16_f32 v75, v72, v73
	v_mad_i64_i32 v[72:73], s[16:17], v80, s4, v[120:121]
	v_lshl_add_u64 v[72:73], v[72:73], 0, v[122:123]
	global_store_dwordx2 v[72:73], v[74:75], off nt
	v_mul_f32_e32 v74, 0xbfb8aa3b, v68
	v_mul_f32_e32 v75, 0xbfb8aa3b, v70
	v_exp_f32_e32 v74, v74
	v_exp_f32_e32 v75, v75
	v_mov_b32_e32 v76, v68
	v_mov_b32_e32 v77, v70
	v_add_f32_e32 v74, 1.0, v74
	v_add_f32_e32 v75, 1.0, v75
	v_rcp_f32_e32 v74, v74
	v_rcp_f32_e32 v75, v75
	v_mov_b32_e32 v70, v69
	v_pk_mul_f32 v[74:75], v[76:77], v[74:75]
	s_nop 0
	v_pk_mul_f32 v[68:69], v[70:71], v[74:75]
	v_mul_f32_e32 v70, 0xbfb8aa3b, v64
	v_mul_f32_e32 v71, 0xbfb8aa3b, v66
	v_exp_f32_e32 v70, v70
	v_exp_f32_e32 v71, v71
	v_mov_b32_e32 v74, v64
	v_mov_b32_e32 v75, v66
	v_add_f32_e32 v70, 1.0, v70
	v_add_f32_e32 v71, 1.0, v71
	v_rcp_f32_e32 v70, v70
	v_rcp_f32_e32 v71, v71
	v_mov_b32_e32 v66, v65
	v_pk_mul_f32 v[70:71], v[74:75], v[70:71]
	s_nop 0
	v_pk_mul_f32 v[64:65], v[66:67], v[70:71]
	v_cvt_pk_bf16_f32 v66, v68, v69
	v_cvt_pk_bf16_f32 v67, v64, v65
	v_add_u32_e32 v64, 0x80, v142
	global_store_dwordx2 v[72:73], v[66:67], off offset:128 nt
	v_ashrrev_i32_e32 v65, 31, v64
	s_waitcnt vmcnt(11)
	v_mov_b32_e32 v66, v220
	v_mov_b32_e32 v67, v221
	v_mov_b32_e32 v128, v67
	v_lshlrev_b64 v[68:69], s14, v[128:129]
	v_min_u32_e32 v65, 1, v68
	v_or_b32_e32 v65, v69, v65
	v_cvt_f32_u32_e32 v65, v65
	v_cvt_f32_u32_e32 v66, v66
	v_ldexp_f32 v65, v65, s15
	v_fmac_f32_e32 v65, 0x2f800000, v66
	v_fmamk_f32 v65, v65, 0x3a000000, v195
	v_cmp_gt_f32_e32 vcc, s27, v65
	v_mul_f32_e32 v66, 0x4b800000, v65
	s_nop 0
	v_cndmask_b32_e32 v65, v65, v66, vcc
	v_rsq_f32_e32 v65, v65
	s_nop 0
	v_mul_f32_e32 v66, 0x45800000, v65
	v_cndmask_b32_e32 v66, v65, v66, vcc
	v_pk_mul_f32 v[60:61], v[60:61], v[66:67] op_sel_hi:[1,0]
	v_pk_mul_f32 v[62:63], v[62:63], v[66:67] op_sel_hi:[1,0]
	v_mul_f32_e32 v65, 0xbfb8aa3b, v60
	v_exp_f32_e32 v65, v65
	v_mov_b32_e32 v70, v60
	v_mov_b32_e32 v71, v62
	v_pk_mul_f32 v[58:59], v[58:59], v[66:67] op_sel_hi:[1,0]
	v_add_f32_e32 v65, 1.0, v65
	v_rcp_f32_e32 v68, v65
	v_mul_f32_e32 v65, 0xbfb8aa3b, v62
	v_exp_f32_e32 v65, v65
	v_pk_mul_f32 v[56:57], v[56:57], v[66:67] op_sel_hi:[1,0]
	v_mov_b32_e32 v62, v61
	v_pk_mul_f32 v[54:55], v[54:55], v[66:67] op_sel_hi:[1,0]
	v_add_f32_e32 v65, 1.0, v65
	v_rcp_f32_e32 v69, v65
	v_pk_mul_f32 v[52:53], v[52:53], v[66:67] op_sel_hi:[1,0]
	v_pk_mul_f32 v[50:51], v[50:51], v[66:67] op_sel_hi:[1,0]
	v_pk_mul_f32 v[48:49], v[48:49], v[66:67] op_sel_hi:[1,0]
	v_pk_mul_f32 v[68:69], v[70:71], v[68:69]
	s_nop 0
	v_pk_mul_f32 v[60:61], v[62:63], v[68:69]
	v_mul_f32_e32 v62, 0xbfb8aa3b, v56
	v_mul_f32_e32 v63, 0xbfb8aa3b, v58
	v_exp_f32_e32 v62, v62
	v_exp_f32_e32 v63, v63
	v_mov_b32_e32 v68, v56
	v_mov_b32_e32 v69, v58
	v_add_f32_e32 v62, 1.0, v62
	v_add_f32_e32 v63, 1.0, v63
	v_rcp_f32_e32 v62, v62
	v_rcp_f32_e32 v63, v63
	v_mov_b32_e32 v58, v57
	v_pk_mul_f32 v[62:63], v[68:69], v[62:63]
	s_nop 0
	v_pk_mul_f32 v[56:57], v[58:59], v[62:63]
	v_cvt_pk_bf16_f32 v58, v60, v61
	v_cvt_pk_bf16_f32 v59, v56, v57
	v_mad_i64_i32 v[56:57], s[16:17], v64, s4, v[120:121]
	v_lshl_add_u64 v[56:57], v[56:57], 0, v[122:123]
	global_store_dwordx2 v[56:57], v[58:59], off nt
	v_mul_f32_e32 v58, 0xbfb8aa3b, v52
	v_mul_f32_e32 v59, 0xbfb8aa3b, v54
	v_exp_f32_e32 v58, v58
	v_exp_f32_e32 v59, v59
	v_mov_b32_e32 v60, v52
	v_mov_b32_e32 v61, v54
	v_add_f32_e32 v58, 1.0, v58
	v_add_f32_e32 v59, 1.0, v59
	v_rcp_f32_e32 v58, v58
	v_rcp_f32_e32 v59, v59
	v_mov_b32_e32 v54, v53
	v_pk_mul_f32 v[58:59], v[60:61], v[58:59]
	s_nop 0
	v_pk_mul_f32 v[52:53], v[54:55], v[58:59]
	v_mul_f32_e32 v54, 0xbfb8aa3b, v48
	v_mul_f32_e32 v55, 0xbfb8aa3b, v50
	v_exp_f32_e32 v54, v54
	v_exp_f32_e32 v55, v55
	v_mov_b32_e32 v58, v48
	v_mov_b32_e32 v59, v50
	v_add_f32_e32 v54, 1.0, v54
	v_add_f32_e32 v55, 1.0, v55
	v_rcp_f32_e32 v54, v54
	v_rcp_f32_e32 v55, v55
	v_mov_b32_e32 v50, v49
	v_pk_mul_f32 v[54:55], v[58:59], v[54:55]
	s_nop 0
	v_pk_mul_f32 v[48:49], v[50:51], v[54:55]
	v_cvt_pk_bf16_f32 v50, v52, v53
	v_cvt_pk_bf16_f32 v51, v48, v49
	v_add_u32_e32 v48, 0x90, v142
	global_store_dwordx2 v[56:57], v[50:51], off offset:128 nt
	v_ashrrev_i32_e32 v49, 31, v48
	s_waitcnt vmcnt(12)
; DI float ss_get(const ssacc_t* p) { const ssacc_t v = *p; return (float)(unsigned)(v >> 32) + (float)(unsigned)(v & 0xffffffffull) * 2.3283064365386963e-10f; }
; DI unsigned cvtpk(float lo, float hi) { f32x2 v = {lo, hi}; bf16x2_t b = __builtin_convertvector(v, bf16x2_t); return __builtin_bit_cast(unsigned, b); }
; DI float sigmoidf_(float x) { return __builtin_amdgcn_rcpf(1.f + fexp2(-LOG2E * x)); }
;     DI void operator()(const Acc& acc, const Unit& u, int wr, int wc, int fr, int fq) const {
;     ...
;         for (int ai = 0; ai < 2; ++ai)
; #pragma unroll
;             for (int m = 0; m < 4; ++m) {
;                 asm volatile("" ::: "memory");
;                 const int row = u.pm * 256 + ai * 128 + wr * 64 + m * 16 + fr;
;                 const float rs = rsqrtf(ss_get(ssx1 + row) * (1.f / 2048.f) + EPS_);
; #pragma unroll
;                 for (int bj = 0; bj < 2; ++bj) {
;                     const f32x4 v0 = acc[ai][bj][m][0] * rs, v1 = acc[ai][bj][m][1] * rs;
;                     const int i0 = (u.pn * 256 + bj * 128 + wc * 32 + 8 * fq) >> 1;
;                     const float o0 = v0[0] * sigmoidf_(v0[0]) * v0[1], o1 = v0[2] * sigmoidf_(v0[2]) * v0[3];
;                     const float o2 = v1[0] * sigmoidf_(v1[0]) * v1[1], o3 = v1[2] * sigmoidf_(v1[2]) * v1[3];
;                     u32x2 w; w.x = cvtpk(o0, o1); w.y = cvtpk(o2, o3);
;                     *(u32x2*)(HM + (size_t)row * DFF_ + i0) = w;
;                 }
;             }
	v_mov_b32_e32 v50, v222
	v_mov_b32_e32 v51, v223
	v_mov_b32_e32 v128, v51
	v_lshlrev_b64 v[52:53], s14, v[128:129]
	v_min_u32_e32 v49, 1, v52
	v_or_b32_e32 v49, v53, v49
	v_cvt_f32_u32_e32 v49, v49
	v_cvt_f32_u32_e32 v50, v50
	v_ldexp_f32 v49, v49, s15
	v_fmac_f32_e32 v49, 0x2f800000, v50
	v_fmamk_f32 v49, v49, 0x3a000000, v195
	v_cmp_gt_f32_e32 vcc, s27, v49
	v_mul_f32_e32 v50, 0x4b800000, v49
	s_nop 0
	v_cndmask_b32_e32 v49, v49, v50, vcc
	v_rsq_f32_e32 v49, v49
	s_nop 0
	v_mul_f32_e32 v50, 0x45800000, v49
	v_cndmask_b32_e32 v50, v49, v50, vcc
	v_pk_mul_f32 v[44:45], v[44:45], v[50:51] op_sel_hi:[1,0]
	v_pk_mul_f32 v[46:47], v[46:47], v[50:51] op_sel_hi:[1,0]
	v_mul_f32_e32 v49, 0xbfb8aa3b, v44
	v_exp_f32_e32 v49, v49
	v_mov_b32_e32 v54, v44
	v_mov_b32_e32 v55, v46
	v_pk_mul_f32 v[42:43], v[42:43], v[50:51] op_sel_hi:[1,0]
	v_add_f32_e32 v49, 1.0, v49
	v_rcp_f32_e32 v52, v49
	v_mul_f32_e32 v49, 0xbfb8aa3b, v46
	v_exp_f32_e32 v49, v49
	v_pk_mul_f32 v[40:41], v[40:41], v[50:51] op_sel_hi:[1,0]
	v_mov_b32_e32 v46, v45
	v_pk_mul_f32 v[38:39], v[38:39], v[50:51] op_sel_hi:[1,0]
	v_add_f32_e32 v49, 1.0, v49
	v_rcp_f32_e32 v53, v49
	v_pk_mul_f32 v[36:37], v[36:37], v[50:51] op_sel_hi:[1,0]
	v_pk_mul_f32 v[34:35], v[34:35], v[50:51] op_sel_hi:[1,0]
	v_pk_mul_f32 v[32:33], v[32:33], v[50:51] op_sel_hi:[1,0]
	v_pk_mul_f32 v[52:53], v[54:55], v[52:53]
	s_nop 0
	v_pk_mul_f32 v[44:45], v[46:47], v[52:53]
	v_mul_f32_e32 v46, 0xbfb8aa3b, v40
	v_mul_f32_e32 v47, 0xbfb8aa3b, v42
	v_exp_f32_e32 v46, v46
	v_exp_f32_e32 v47, v47
	v_mov_b32_e32 v52, v40
	v_mov_b32_e32 v53, v42
	v_add_f32_e32 v46, 1.0, v46
	v_add_f32_e32 v47, 1.0, v47
	v_rcp_f32_e32 v46, v46
	v_rcp_f32_e32 v47, v47
	v_mov_b32_e32 v42, v41
	v_pk_mul_f32 v[46:47], v[52:53], v[46:47]
	s_nop 0
	v_pk_mul_f32 v[40:41], v[42:43], v[46:47]
	v_cvt_pk_bf16_f32 v42, v44, v45
	v_cvt_pk_bf16_f32 v43, v40, v41
	v_mad_i64_i32 v[40:41], s[16:17], v48, s4, v[120:121]
	v_lshl_add_u64 v[40:41], v[40:41], 0, v[122:123]
	global_store_dwordx2 v[40:41], v[42:43], off nt
	v_mul_f32_e32 v42, 0xbfb8aa3b, v36
	v_mul_f32_e32 v43, 0xbfb8aa3b, v38
	v_exp_f32_e32 v42, v42
	v_exp_f32_e32 v43, v43
	v_mov_b32_e32 v44, v36
	v_mov_b32_e32 v45, v38
	v_add_f32_e32 v42, 1.0, v42
	v_add_f32_e32 v43, 1.0, v43
	v_rcp_f32_e32 v42, v42
	v_rcp_f32_e32 v43, v43
	v_mov_b32_e32 v38, v37
	v_pk_mul_f32 v[42:43], v[44:45], v[42:43]
	s_nop 0
	v_pk_mul_f32 v[36:37], v[38:39], v[42:43]
	v_mul_f32_e32 v38, 0xbfb8aa3b, v32
	v_mul_f32_e32 v39, 0xbfb8aa3b, v34
	v_exp_f32_e32 v38, v38
	v_exp_f32_e32 v39, v39
	v_mov_b32_e32 v42, v32
	v_mov_b32_e32 v43, v34
	v_add_f32_e32 v38, 1.0, v38
	v_add_f32_e32 v39, 1.0, v39
	v_rcp_f32_e32 v38, v38
	v_rcp_f32_e32 v39, v39
	v_mov_b32_e32 v34, v33
	v_pk_mul_f32 v[38:39], v[42:43], v[38:39]
	s_nop 0
	v_pk_mul_f32 v[32:33], v[34:35], v[38:39]
	v_cvt_pk_bf16_f32 v34, v36, v37
	v_cvt_pk_bf16_f32 v35, v32, v33
	v_add_u32_e32 v32, 0xa0, v142
	global_store_dwordx2 v[40:41], v[34:35], off offset:128 nt
	v_ashrrev_i32_e32 v33, 31, v32
	s_waitcnt vmcnt(13)
; DI float ss_get(const ssacc_t* p) { const ssacc_t v = *p; return (float)(unsigned)(v >> 32) + (float)(unsigned)(v & 0xffffffffull) * 2.3283064365386963e-10f; }
; DI unsigned cvtpk(float lo, float hi) { f32x2 v = {lo, hi}; bf16x2_t b = __builtin_convertvector(v, bf16x2_t); return __builtin_bit_cast(unsigned, b); }
; DI float sigmoidf_(float x) { return __builtin_amdgcn_rcpf(1.f + fexp2(-LOG2E * x)); }
;     DI void operator()(const Acc& acc, const Unit& u, int wr, int wc, int fr, int fq) const {
;     ...
;         for (int ai = 0; ai < 2; ++ai)
; #pragma unroll
;             for (int m = 0; m < 4; ++m) {
;                 asm volatile("" ::: "memory");
;                 const int row = u.pm * 256 + ai * 128 + wr * 64 + m * 16 + fr;
;                 const float rs = rsqrtf(ss_get(ssx1 + row) * (1.f / 2048.f) + EPS_);
; #pragma unroll
;                 for (int bj = 0; bj < 2; ++bj) {
;                     const f32x4 v0 = acc[ai][bj][m][0] * rs, v1 = acc[ai][bj][m][1] * rs;
;                     const int i0 = (u.pn * 256 + bj * 128 + wc * 32 + 8 * fq) >> 1;
;                     const float o0 = v0[0] * sigmoidf_(v0[0]) * v0[1], o1 = v0[2] * sigmoidf_(v0[2]) * v0[3];
;                     const float o2 = v1[0] * sigmoidf_(v1[0]) * v1[1], o3 = v1[2] * sigmoidf_(v1[2]) * v1[3];
;                     u32x2 w; w.x = cvtpk(o0, o1); w.y = cvtpk(o2, o3);
;                     *(u32x2*)(HM + (size_t)row * DFF_ + i0) = w;
;                 }
;             }
	v_mov_b32_e32 v34, v224
	v_mov_b32_e32 v35, v225
	v_mov_b32_e32 v128, v35
	v_lshlrev_b64 v[36:37], s14, v[128:129]
	v_min_u32_e32 v33, 1, v36
	v_or_b32_e32 v33, v37, v33
	v_cvt_f32_u32_e32 v33, v33
	v_cvt_f32_u32_e32 v34, v34
	v_ldexp_f32 v33, v33, s15
	v_fmac_f32_e32 v33, 0x2f800000, v34
	v_fmamk_f32 v33, v33, 0x3a000000, v195
	v_cmp_gt_f32_e32 vcc, s27, v33
	v_mul_f32_e32 v34, 0x4b800000, v33
	s_nop 0
	v_cndmask_b32_e32 v33, v33, v34, vcc
	v_rsq_f32_e32 v33, v33
	s_nop 0
	v_mul_f32_e32 v34, 0x45800000, v33
	v_cndmask_b32_e32 v34, v33, v34, vcc
	v_pk_mul_f32 v[28:29], v[28:29], v[34:35] op_sel_hi:[1,0]
	v_pk_mul_f32 v[30:31], v[30:31], v[34:35] op_sel_hi:[1,0]
	v_mul_f32_e32 v33, 0xbfb8aa3b, v28
	v_exp_f32_e32 v33, v33
	v_mov_b32_e32 v38, v28
	v_mov_b32_e32 v39, v30
	v_pk_mul_f32 v[26:27], v[26:27], v[34:35] op_sel_hi:[1,0]
	v_add_f32_e32 v33, 1.0, v33
	v_rcp_f32_e32 v36, v33
	v_mul_f32_e32 v33, 0xbfb8aa3b, v30
	v_exp_f32_e32 v33, v33
	v_pk_mul_f32 v[24:25], v[24:25], v[34:35] op_sel_hi:[1,0]
	v_mov_b32_e32 v30, v29
	v_pk_mul_f32 v[22:23], v[22:23], v[34:35] op_sel_hi:[1,0]
	v_add_f32_e32 v33, 1.0, v33
	v_rcp_f32_e32 v37, v33
	v_pk_mul_f32 v[20:21], v[20:21], v[34:35] op_sel_hi:[1,0]
	v_pk_mul_f32 v[18:19], v[18:19], v[34:35] op_sel_hi:[1,0]
	v_pk_mul_f32 v[16:17], v[16:17], v[34:35] op_sel_hi:[1,0]
	v_pk_mul_f32 v[36:37], v[38:39], v[36:37]
	s_nop 0
	v_pk_mul_f32 v[28:29], v[30:31], v[36:37]
	v_mul_f32_e32 v30, 0xbfb8aa3b, v24
	v_mul_f32_e32 v31, 0xbfb8aa3b, v26
	v_exp_f32_e32 v30, v30
	v_exp_f32_e32 v31, v31
	v_mov_b32_e32 v36, v24
	v_mov_b32_e32 v37, v26
	v_add_f32_e32 v30, 1.0, v30
	v_add_f32_e32 v31, 1.0, v31
	v_rcp_f32_e32 v30, v30
	v_rcp_f32_e32 v31, v31
	v_mov_b32_e32 v26, v25
	v_pk_mul_f32 v[30:31], v[36:37], v[30:31]
	s_nop 0
	v_pk_mul_f32 v[24:25], v[26:27], v[30:31]
	v_cvt_pk_bf16_f32 v26, v28, v29
	v_cvt_pk_bf16_f32 v27, v24, v25
	v_mad_i64_i32 v[24:25], s[16:17], v32, s4, v[120:121]
	v_lshl_add_u64 v[24:25], v[24:25], 0, v[122:123]
	global_store_dwordx2 v[24:25], v[26:27], off nt
	v_mul_f32_e32 v26, 0xbfb8aa3b, v20
	v_mul_f32_e32 v27, 0xbfb8aa3b, v22
	v_exp_f32_e32 v26, v26
	v_exp_f32_e32 v27, v27
	v_mov_b32_e32 v28, v20
	v_mov_b32_e32 v29, v22
	v_add_f32_e32 v26, 1.0, v26
	v_add_f32_e32 v27, 1.0, v27
	v_rcp_f32_e32 v26, v26
	v_rcp_f32_e32 v27, v27
	v_mov_b32_e32 v22, v21
	v_pk_mul_f32 v[26:27], v[28:29], v[26:27]
	s_nop 0
	v_pk_mul_f32 v[20:21], v[22:23], v[26:27]
	v_mul_f32_e32 v22, 0xbfb8aa3b, v16
	v_mul_f32_e32 v23, 0xbfb8aa3b, v18
	v_exp_f32_e32 v22, v22
	v_exp_f32_e32 v23, v23
	v_mov_b32_e32 v26, v16
	v_mov_b32_e32 v27, v18
	v_add_f32_e32 v22, 1.0, v22
	v_add_f32_e32 v23, 1.0, v23
	v_rcp_f32_e32 v22, v22
	v_rcp_f32_e32 v23, v23
	v_mov_b32_e32 v18, v17
	v_pk_mul_f32 v[22:23], v[26:27], v[22:23]
	s_nop 0
	v_pk_mul_f32 v[16:17], v[18:19], v[22:23]
	v_cvt_pk_bf16_f32 v18, v20, v21
	v_cvt_pk_bf16_f32 v19, v16, v17
	v_add_u32_e32 v16, 0xb0, v142
	global_store_dwordx2 v[24:25], v[18:19], off offset:128 nt
	v_ashrrev_i32_e32 v17, 31, v16
	s_waitcnt vmcnt(14)
	v_mov_b32_e32 v18, v226
	v_mov_b32_e32 v19, v227
	v_mov_b32_e32 v128, v19
	v_lshlrev_b64 v[20:21], s14, v[128:129]
	v_min_u32_e32 v17, 1, v20
	v_or_b32_e32 v17, v21, v17
	v_cvt_f32_u32_e32 v17, v17
	v_cvt_f32_u32_e32 v18, v18
	v_ldexp_f32 v17, v17, s15
	v_fmac_f32_e32 v17, 0x2f800000, v18
	v_fmamk_f32 v17, v17, 0x3a000000, v195
	v_cmp_gt_f32_e32 vcc, s27, v17
	v_mul_f32_e32 v18, 0x4b800000, v17
	s_nop 0
	v_cndmask_b32_e32 v17, v17, v18, vcc
	v_rsq_f32_e32 v17, v17
	s_nop 0
	v_mul_f32_e32 v18, 0x45800000, v17
	v_cndmask_b32_e32 v18, v17, v18, vcc
	v_pk_mul_f32 v[12:13], v[12:13], v[18:19] op_sel_hi:[1,0]
	v_pk_mul_f32 v[14:15], v[14:15], v[18:19] op_sel_hi:[1,0]
	v_mul_f32_e32 v17, 0xbfb8aa3b, v12
	v_exp_f32_e32 v17, v17
	v_mov_b32_e32 v22, v12
	v_mov_b32_e32 v23, v14
	v_pk_mul_f32 v[10:11], v[10:11], v[18:19] op_sel_hi:[1,0]
	v_add_f32_e32 v17, 1.0, v17
	v_rcp_f32_e32 v20, v17
	v_mul_f32_e32 v17, 0xbfb8aa3b, v14
	v_exp_f32_e32 v17, v17
	v_pk_mul_f32 v[8:9], v[8:9], v[18:19] op_sel_hi:[1,0]
	v_mov_b32_e32 v14, v13
	v_pk_mul_f32 v[6:7], v[6:7], v[18:19] op_sel_hi:[1,0]
	v_add_f32_e32 v17, 1.0, v17
	v_rcp_f32_e32 v21, v17
	v_pk_mul_f32 v[4:5], v[4:5], v[18:19] op_sel_hi:[1,0]
	v_pk_mul_f32 v[2:3], v[2:3], v[18:19] op_sel_hi:[1,0]
	v_pk_mul_f32 v[0:1], v[0:1], v[18:19] op_sel_hi:[1,0]
	v_pk_mul_f32 v[20:21], v[22:23], v[20:21]
	s_and_b64 vcc, exec, s[48:49]
	v_pk_mul_f32 v[12:13], v[14:15], v[20:21]
	v_mul_f32_e32 v14, 0xbfb8aa3b, v8
	v_mul_f32_e32 v15, 0xbfb8aa3b, v10
	v_exp_f32_e32 v14, v14
	v_exp_f32_e32 v15, v15
	v_mov_b32_e32 v20, v8
	v_mov_b32_e32 v21, v10
	v_add_f32_e32 v14, 1.0, v14
	v_add_f32_e32 v15, 1.0, v15
	v_rcp_f32_e32 v14, v14
	v_rcp_f32_e32 v15, v15
	v_mov_b32_e32 v10, v9
	v_pk_mul_f32 v[14:15], v[20:21], v[14:15]
	s_nop 0
	v_pk_mul_f32 v[8:9], v[10:11], v[14:15]
	v_cvt_pk_bf16_f32 v10, v12, v13
	v_cvt_pk_bf16_f32 v11, v8, v9
	v_mad_i64_i32 v[8:9], s[14:15], v16, s4, v[120:121]
	v_lshl_add_u64 v[8:9], v[8:9], 0, v[122:123]
	global_store_dwordx2 v[8:9], v[10:11], off nt
	v_mul_f32_e32 v10, 0xbfb8aa3b, v4
	v_mul_f32_e32 v11, 0xbfb8aa3b, v6
	v_exp_f32_e32 v10, v10
	v_exp_f32_e32 v11, v11
	v_mov_b32_e32 v12, v4
	v_mov_b32_e32 v13, v6
	v_add_f32_e32 v10, 1.0, v10
	v_add_f32_e32 v11, 1.0, v11
	v_rcp_f32_e32 v10, v10
	v_rcp_f32_e32 v11, v11
	v_mov_b32_e32 v6, v5
	s_mov_b64 s[14:15], -1
	v_pk_mul_f32 v[10:11], v[12:13], v[10:11]
	s_nop 0
	v_pk_mul_f32 v[4:5], v[6:7], v[10:11]
	v_mul_f32_e32 v6, 0xbfb8aa3b, v0
	v_mul_f32_e32 v7, 0xbfb8aa3b, v2
	v_exp_f32_e32 v6, v6
	v_exp_f32_e32 v7, v7
	v_mov_b32_e32 v10, v0
	v_mov_b32_e32 v11, v2
	v_add_f32_e32 v6, 1.0, v6
	v_add_f32_e32 v7, 1.0, v7
	v_rcp_f32_e32 v6, v6
	v_rcp_f32_e32 v7, v7
	v_mov_b32_e32 v2, v1
	v_pk_mul_f32 v[6:7], v[10:11], v[6:7]
	s_nop 0
	v_pk_mul_f32 v[0:1], v[2:3], v[6:7]
	v_cvt_pk_bf16_f32 v2, v4, v5
	v_cvt_pk_bf16_f32 v3, v0, v1
	global_store_dwordx2 v[8:9], v[2:3], off offset:128 nt
	s_cbranch_vccnz .LBB0_1356
	s_andn2_b64 vcc, exec, s[42:43]
	s_cbranch_vccnz .LBB0_1355
	s_barrier
	s_branch .LBB0_1355
